# v28: v25 + rwkv scan phase write-through with flat barrier
# speedup vs baseline: 1.0054x; 1.0054x over previous
.LBB0_2908:
	s_add_i32 s49, s73, s49
	s_lshl_b32 s49, s49, 11
	s_nop 4
	buffer_store_dword v22, v52, s[20:23], s49 offen sc1
	s_add_i32 s49, s40, s73
	s_lshl_b32 s49, s49, 11
	buffer_store_dword v23, v52, s[20:23], s49 offen sc1
	s_sub_i32 s49, s73, s87
	s_lshl_b32 s49, s49, 11
	s_add_i32 s48, s73, s48
	s_addk_i32 s49, 0x1000
	s_lshl_b32 s48, s48, 11
	s_add_i32 s47, s47, 2
	s_addk_i32 s44, 0x7000
	s_sub_i32 s46, s46, 32
	s_add_i32 s45, s45, 32
	v_pk_mul_f32 v[8:9], v[16:17], v[40:41]
	v_pk_mul_f32 v[6:7], v[14:15], v[38:39]
	v_pk_mul_f32 v[12:13], v[12:13], v[36:37]
	v_pk_mul_f32 v[10:11], v[10:11], v[34:35]
	s_waitcnt lgkmcnt(1)
	v_pk_mul_f32 v[16:17], v[20:21], v[32:33]
	v_pk_mul_f32 v[14:15], v[18:19], v[30:31]
	s_waitcnt lgkmcnt(0)
	v_pk_mul_f32 v[20:21], v[44:45], v[28:29]
	v_pk_mul_f32 v[18:19], v[42:43], v[26:27]
	s_cmp_eq_u32 s44, 0
	buffer_store_dword v24, v52, s[20:23], s49 offen sc1
	buffer_store_dword v25, v52, s[20:23], s48 offen sc1
	s_cbranch_scc1 .LBB0_2906

.LBB0_2911:
	s_waitcnt lgkmcnt(0)
	s_nop 0
	v_pk_mul_f32 v[58:59], v[18:19], v[10:11]
	v_add_u32_e32 v3, 0x11800, v44
	v_add_u32_e32 v5, 0x11820, v44
	v_add_u32_e32 v10, 0x12100, v44
	v_pk_mul_f32 v[60:61], v[20:21], v[12:13]
	v_add_u32_e32 v11, 0x12120, v44
	ds_read_b64 v[18:19], v3
	ds_read_b64 v[20:21], v5
	ds_read_b64 v[62:63], v10
	ds_read_b64 v[64:65], v11
	v_add_u32_e32 v3, 0x11840, v44
	v_add_u32_e32 v5, 0x11860, v44
	v_add_u32_e32 v10, 0x12140, v44
	v_pk_mul_f32 v[28:29], v[40:41], v[28:29]
	v_pk_mul_f32 v[26:27], v[38:39], v[26:27]
	v_pk_mul_f32 v[24:25], v[36:37], v[24:25]
	v_pk_mul_f32 v[22:23], v[34:35], v[22:23]
	v_add_u32_e32 v11, 0x12160, v44
	ds_read_b64 v[34:35], v3
	ds_read_b64 v[36:37], v5
	ds_read_b64 v[66:67], v10
	ds_read_b64 v[68:69], v11
	v_add_u32_e32 v3, 0x11800, v45
	v_add_u32_e32 v5, 0x12c00, v42
	v_add_u32_e32 v10, 0x11800, v2
	v_add_u32_e32 v11, 0x11820, v2
	ds_read_b64 v[38:39], v3
	ds_read_b64 v[2:3], v5
	ds_read_b64 v[70:71], v10
	ds_read_b64 v[72:73], v11
	v_add_u32_e32 v5, 0x11800, v43
	v_add_u32_e32 v10, 0x11800, v42
	v_cvt_pk_bf16_f32 v130, v26, v27
	v_cvt_pk_bf16_f32 v131, v28, v29
	v_cvt_pk_bf16_f32 v132, v22, v23
	v_cvt_pk_bf16_f32 v133, v24, v25
	v_pk_mul_f32 v[32:33], v[32:33], v[16:17]
	v_pk_mul_f32 v[30:31], v[30:31], v[14:15]
	v_add_u32_e32 v11, 0x12200, v42
	ds_read_b64 v[74:75], v10
	ds_read_b128 v[14:17], v5
	v_add_u32_e32 v5, 0x11a80, v42
	s_waitcnt lgkmcnt(12)
	v_mfma_f32_16x16x32_bf16 v[18:21], v[18:21], v[130:133], 0
	v_add_u32_e32 v10, 0x12480, v42
	ds_read_b64 v[76:77], v11
	ds_read_b64 v[122:123], v5
	ds_read_b64 v[124:125], v10
	v_add_u32_e32 v5, 0x11840, v43
	v_add_u32_e32 v40, 0x11d00, v42
	ds_read_b128 v[10:13], v5
	ds_read_b64 v[126:127], v40
	v_add_u32_e32 v5, 0x12700, v42
	ds_read_b64 v[128:129], v5
	v_cvt_pk_bf16_f32 v134, v30, v31
	v_cvt_pk_bf16_f32 v135, v32, v33
	v_cvt_pk_bf16_f32 v136, v58, v59
	v_cvt_pk_bf16_f32 v137, v60, v61
	v_mov_b32_e32 v5, v4
	s_waitcnt lgkmcnt(11)
	v_mov_b32_e32 v40, v38
	v_mfma_f32_16x16x32_bf16 v[18:21], v[34:37], v[134:137], v[18:21]
	v_mov_b32_e32 v41, v39
	v_add_u32_e32 v34, 0x11f80, v42
	v_mov_b32_e32 v140, v38
	s_waitcnt lgkmcnt(10)
	v_mfma_f32_16x16x32_bf16 v[18:21], v[2:5], v[38:41], v[18:21]
	v_mov_b32_e32 v141, v39
	v_add_u32_e32 v2, 0x12980, v42
	s_add_i32 s75, s74, s75
	s_lshl_b32 s75, s75, 11
	s_add_i32 s73, s74, s73
	s_waitcnt vmcnt(1)
	s_nop 1
	v_cvt_pk_bf16_f32 v138, v18, v19
	v_cvt_pk_bf16_f32 v139, v20, v21
	s_lshl_b32 s73, s73, 11
	s_andn2_b64 vcc, exec, s[16:17]
	s_waitcnt lgkmcnt(5)
	v_mfma_f32_16x16x32_bf16 v[38:41], v[74:77], v[138:141], v[26:29]
	s_nop 2
	ds_read_b64 v[26:27], v34
	ds_read_b64 v[28:29], v2
	v_add_u32_e32 v2, 0x11880, v43
	buffer_store_dword v6, v52, s[20:23], s75 offen sc1
	s_waitcnt lgkmcnt(5)
	v_mfma_f32_16x16x32_bf16 v[34:37], v[122:125], v[138:141], v[22:25]
	ds_read_b128 v[18:21], v2
	s_add_i32 s75, s40, s74
	v_add_u32_e32 v2, 0x118c0, v43
	v_mfma_f32_16x16x32_bf16 v[22:25], v[62:65], v[130:133], 0
	s_lshl_b32 s75, s75, 11
	ds_read_b128 v[42:45], v2
	buffer_store_dword v7, v52, s[20:23], s75 offen sc1
	v_mfma_f32_16x16x32_bf16 v[22:25], v[66:69], v[134:137], v[22:25]
	s_sub_i32 s75, s74, s87
	s_lshl_b32 s75, s75, 11
	s_addk_i32 s75, 0x1000
	s_waitcnt lgkmcnt(4)
	v_mfma_f32_16x16x32_bf16 v[30:33], v[126:129], v[138:141], v[30:33]
	buffer_store_dword v8, v52, s[20:23], s75 offen sc1
	buffer_store_dword v9, v52, s[20:23], s73 offen sc1
	s_mov_b32 s73, s46
	s_waitcnt lgkmcnt(2)
	v_mfma_f32_16x16x32_bf16 v[26:29], v[26:29], v[138:141], v[58:61]
	v_mfma_f32_16x16x32_bf16 v[22:25], v[70:73], v[138:141], v[22:25]
	s_cbranch_vccnz .LBB0_2908
	s_lshl_b32 s48, s47, 4
	s_add_i32 s48, s43, s48
	s_add_i32 s73, s48, 16
	s_mov_b32 s49, 0
	s_mov_b32 s48, 3
	s_branch .LBB0_2908
.LBB0_2913:
	ds_read_b64 v[2:3], v4 offset:408
	s_and_b32 s16, s36, 0x3fffff0
	s_lshl_b32 s17, s87, 3
	s_or_b32 s18, s17, s16
	s_or_b32 s18, s18, s26
	s_waitcnt lgkmcnt(0)
	v_readfirstlane_b32 s16, v2
	v_readfirstlane_b32 s17, v3
	v_lshl_or_b32 v2, s18, 6, v49
	v_mov_b32_e32 v3, v4
	v_lshlrev_b64 v[2:3], 8, v[2:3]
	v_lshl_add_u64 v[2:3], s[16:17], 0, v[2:3]
	v_lshlrev_b32_e32 v22, 2, v46
	v_mov_b32_e32 v23, v4
	v_lshl_add_u64 v[2:3], v[2:3], 0, v[22:23]
	v_lshl_add_u64 v[22:23], v[2:3], 0, s[34:35]
	v_add_co_u32_e32 v2, vcc, 0x2e80000, v2
	s_mov_b64 s[16:17], 0
	s_nop 0
	v_addc_co_u32_e32 v3, vcc, 0, v3, vcc
	global_store_dwordx4 v[2:3], v[6:9], off sc1
	global_store_dwordx4 v[22:23], v[10:13], off offset:64 sc1
	global_store_dwordx4 v[22:23], v[14:17], off offset:128 sc1
	global_store_dwordx4 v[22:23], v[18:21], off offset:192 sc1

.LBB0_2924:
	s_add_i32 s48, s49, s48
	s_lshl_b32 s48, s48, 11
	s_nop 4
	buffer_store_dword v22, v52, s[20:23], s48 offen sc1
	s_add_i32 s48, s39, s49
	s_lshl_b32 s48, s48, 11
	buffer_store_dword v23, v52, s[20:23], s48 offen sc1
	s_sub_i32 s48, s49, s87
	s_lshl_b32 s48, s48, 11
	s_add_i32 s47, s49, s47
	s_addk_i32 s48, 0x1000
	s_lshl_b32 s47, s47, 11
	s_add_i32 s46, s46, 2
	s_addk_i32 s43, 0x7000
	s_sub_i32 s45, s45, 32
	s_add_i32 s44, s44, 32
	v_pk_mul_f32 v[8:9], v[16:17], v[40:41]
	v_pk_mul_f32 v[6:7], v[14:15], v[38:39]
	v_pk_mul_f32 v[12:13], v[12:13], v[36:37]
	v_pk_mul_f32 v[10:11], v[10:11], v[34:35]
	s_waitcnt lgkmcnt(1)
	v_pk_mul_f32 v[16:17], v[20:21], v[32:33]
	v_pk_mul_f32 v[14:15], v[18:19], v[30:31]
	s_waitcnt lgkmcnt(0)
	v_pk_mul_f32 v[20:21], v[44:45], v[28:29]
	v_pk_mul_f32 v[18:19], v[42:43], v[26:27]
	s_cmp_eq_u32 s43, 0
	buffer_store_dword v24, v52, s[20:23], s48 offen sc1
	buffer_store_dword v25, v52, s[20:23], s47 offen sc1
	s_cbranch_scc1 .LBB0_2922

.LBB0_2927:
	s_waitcnt lgkmcnt(0)
	s_nop 0
	v_pk_mul_f32 v[58:59], v[18:19], v[10:11]
	v_add_u32_e32 v3, 0x11800, v44
	v_add_u32_e32 v5, 0x11820, v44
	v_add_u32_e32 v10, 0x12100, v44
	v_pk_mul_f32 v[60:61], v[20:21], v[12:13]
	v_add_u32_e32 v11, 0x12120, v44
	ds_read_b64 v[18:19], v3
	ds_read_b64 v[20:21], v5
	ds_read_b64 v[62:63], v10
	ds_read_b64 v[64:65], v11
	v_add_u32_e32 v3, 0x11840, v44
	v_add_u32_e32 v5, 0x11860, v44
	v_add_u32_e32 v10, 0x12140, v44
	v_pk_mul_f32 v[28:29], v[40:41], v[28:29]
	v_pk_mul_f32 v[26:27], v[38:39], v[26:27]
	v_pk_mul_f32 v[24:25], v[36:37], v[24:25]
	v_pk_mul_f32 v[22:23], v[34:35], v[22:23]
	v_add_u32_e32 v11, 0x12160, v44
	ds_read_b64 v[34:35], v3
	ds_read_b64 v[36:37], v5
	ds_read_b64 v[66:67], v10
	ds_read_b64 v[68:69], v11
	v_add_u32_e32 v3, 0x11800, v45
	v_add_u32_e32 v5, 0x12c00, v42
	v_add_u32_e32 v10, 0x11800, v2
	v_add_u32_e32 v11, 0x11820, v2
	ds_read_b64 v[38:39], v3
	ds_read_b64 v[2:3], v5
	ds_read_b64 v[70:71], v10
	ds_read_b64 v[72:73], v11
	v_add_u32_e32 v5, 0x11800, v43
	v_add_u32_e32 v10, 0x11800, v42
	v_cvt_pk_bf16_f32 v130, v26, v27
	v_cvt_pk_bf16_f32 v131, v28, v29
	v_cvt_pk_bf16_f32 v132, v22, v23
	v_cvt_pk_bf16_f32 v133, v24, v25
	v_pk_mul_f32 v[32:33], v[32:33], v[16:17]
	v_pk_mul_f32 v[30:31], v[30:31], v[14:15]
	v_add_u32_e32 v11, 0x12200, v42
	ds_read_b64 v[74:75], v10
	ds_read_b128 v[14:17], v5
	v_add_u32_e32 v5, 0x11a80, v42
	s_waitcnt lgkmcnt(12)
	v_mfma_f32_16x16x32_bf16 v[18:21], v[18:21], v[130:133], 0
	v_add_u32_e32 v10, 0x12480, v42
	ds_read_b64 v[76:77], v11
	ds_read_b64 v[122:123], v5
	ds_read_b64 v[124:125], v10
	v_add_u32_e32 v5, 0x11840, v43
	v_add_u32_e32 v40, 0x11d00, v42
	ds_read_b128 v[10:13], v5
	ds_read_b64 v[126:127], v40
	v_add_u32_e32 v5, 0x12700, v42
	ds_read_b64 v[128:129], v5
	v_cvt_pk_bf16_f32 v134, v30, v31
	v_cvt_pk_bf16_f32 v135, v32, v33
	v_cvt_pk_bf16_f32 v136, v58, v59
	v_cvt_pk_bf16_f32 v137, v60, v61
	v_mov_b32_e32 v5, v4
	s_waitcnt lgkmcnt(11)
	v_mov_b32_e32 v40, v38
	v_mfma_f32_16x16x32_bf16 v[18:21], v[34:37], v[134:137], v[18:21]
	v_mov_b32_e32 v41, v39
	v_add_u32_e32 v34, 0x11f80, v42
	v_mov_b32_e32 v140, v38
	s_waitcnt lgkmcnt(10)
	v_mfma_f32_16x16x32_bf16 v[18:21], v[2:5], v[38:41], v[18:21]
	v_mov_b32_e32 v141, v39
	v_add_u32_e32 v2, 0x12980, v42
	s_add_i32 s74, s73, s74
	s_lshl_b32 s74, s74, 11
	s_add_i32 s49, s73, s49
	s_nop 2
	v_cvt_pk_bf16_f32 v138, v18, v19
	v_cvt_pk_bf16_f32 v139, v20, v21
	s_lshl_b32 s49, s49, 11
	s_andn2_b64 vcc, exec, s[16:17]
	s_waitcnt lgkmcnt(5)
	v_mfma_f32_16x16x32_bf16 v[38:41], v[74:77], v[138:141], v[26:29]
	s_nop 2
	ds_read_b64 v[26:27], v34
	ds_read_b64 v[28:29], v2
	v_add_u32_e32 v2, 0x11880, v43
	buffer_store_dword v6, v52, s[20:23], s74 offen sc1
	s_waitcnt lgkmcnt(5)
	v_mfma_f32_16x16x32_bf16 v[34:37], v[122:125], v[138:141], v[22:25]
	ds_read_b128 v[18:21], v2
	s_add_i32 s74, s39, s73
	v_add_u32_e32 v2, 0x118c0, v43
	v_mfma_f32_16x16x32_bf16 v[22:25], v[62:65], v[130:133], 0
	s_lshl_b32 s74, s74, 11
	ds_read_b128 v[42:45], v2
	buffer_store_dword v7, v52, s[20:23], s74 offen sc1
	v_mfma_f32_16x16x32_bf16 v[22:25], v[66:69], v[134:137], v[22:25]
	s_sub_i32 s74, s73, s87
	s_lshl_b32 s74, s74, 11
	s_addk_i32 s74, 0x1000
	s_waitcnt lgkmcnt(4)
	v_mfma_f32_16x16x32_bf16 v[30:33], v[126:129], v[138:141], v[30:33]
	buffer_store_dword v8, v52, s[20:23], s74 offen sc1
	buffer_store_dword v9, v52, s[20:23], s49 offen sc1
	s_mov_b32 s49, s45
	s_waitcnt lgkmcnt(2)
	v_mfma_f32_16x16x32_bf16 v[26:29], v[26:29], v[138:141], v[58:61]
	v_mfma_f32_16x16x32_bf16 v[22:25], v[70:73], v[138:141], v[22:25]
	s_cbranch_vccnz .LBB0_2924
	s_lshl_b32 s47, s46, 4
	s_add_i32 s47, s42, s47
	s_add_i32 s49, s47, 16
	s_mov_b32 s48, 0
	s_mov_b32 s47, 3
	s_branch .LBB0_2924

.LBB0_2947:
	s_add_i32 s48, s49, s48
	s_lshl_b32 s48, s48, 11
	s_nop 4
	buffer_store_dword v22, v52, s[20:23], s48 offen sc1
	s_add_i32 s48, s39, s49
	s_lshl_b32 s48, s48, 11
	buffer_store_dword v23, v52, s[20:23], s48 offen sc1
	s_sub_i32 s48, s49, s88
	s_lshl_b32 s48, s48, 11
	s_add_i32 s47, s49, s47
	s_addk_i32 s48, 0x1000
	s_lshl_b32 s47, s47, 11
	s_add_i32 s46, s46, 2
	s_addk_i32 s43, 0x7000
	s_sub_i32 s45, s45, 32
	s_add_i32 s44, s44, 32
	v_pk_mul_f32 v[8:9], v[16:17], v[40:41]
	v_pk_mul_f32 v[6:7], v[14:15], v[38:39]
	v_pk_mul_f32 v[12:13], v[12:13], v[36:37]
	v_pk_mul_f32 v[10:11], v[10:11], v[34:35]
	s_waitcnt lgkmcnt(1)
	v_pk_mul_f32 v[16:17], v[20:21], v[32:33]
	v_pk_mul_f32 v[14:15], v[18:19], v[30:31]
	s_waitcnt lgkmcnt(0)
	v_pk_mul_f32 v[20:21], v[44:45], v[28:29]
	v_pk_mul_f32 v[18:19], v[42:43], v[26:27]
	s_cmp_eq_u32 s43, 0
	buffer_store_dword v24, v52, s[20:23], s48 offen sc1
	buffer_store_dword v25, v52, s[20:23], s47 offen sc1
	s_cbranch_scc1 .LBB0_2945

.LBB0_2950:
	s_waitcnt lgkmcnt(0)
	s_nop 0
	v_pk_mul_f32 v[58:59], v[18:19], v[10:11]
	v_add_u32_e32 v3, 0x11800, v44
	v_add_u32_e32 v5, 0x11820, v44
	v_add_u32_e32 v10, 0x12100, v44
	v_pk_mul_f32 v[60:61], v[20:21], v[12:13]
	v_add_u32_e32 v11, 0x12120, v44
	ds_read_b64 v[18:19], v3
	ds_read_b64 v[20:21], v5
	ds_read_b64 v[62:63], v10
	ds_read_b64 v[64:65], v11
	v_add_u32_e32 v3, 0x11840, v44
	v_add_u32_e32 v5, 0x11860, v44
	v_add_u32_e32 v10, 0x12140, v44
	v_pk_mul_f32 v[28:29], v[40:41], v[28:29]
	v_pk_mul_f32 v[26:27], v[38:39], v[26:27]
	v_pk_mul_f32 v[24:25], v[36:37], v[24:25]
	v_pk_mul_f32 v[22:23], v[34:35], v[22:23]
	v_add_u32_e32 v11, 0x12160, v44
	ds_read_b64 v[34:35], v3
	ds_read_b64 v[36:37], v5
	ds_read_b64 v[66:67], v10
	ds_read_b64 v[68:69], v11
	v_add_u32_e32 v3, 0x11800, v45
	v_add_u32_e32 v5, 0x12c00, v42
	v_add_u32_e32 v10, 0x11800, v2
	v_add_u32_e32 v11, 0x11820, v2
	ds_read_b64 v[38:39], v3
	ds_read_b64 v[2:3], v5
	ds_read_b64 v[70:71], v10
	ds_read_b64 v[72:73], v11
	v_add_u32_e32 v5, 0x11800, v43
	v_add_u32_e32 v10, 0x11800, v42
	v_cvt_pk_bf16_f32 v128, v26, v27
	v_cvt_pk_bf16_f32 v129, v28, v29
	v_cvt_pk_bf16_f32 v130, v22, v23
	v_cvt_pk_bf16_f32 v131, v24, v25
	v_pk_mul_f32 v[32:33], v[32:33], v[16:17]
	v_pk_mul_f32 v[30:31], v[30:31], v[14:15]
	v_add_u32_e32 v11, 0x12200, v42
	ds_read_b64 v[74:75], v10
	ds_read_b128 v[14:17], v5
	v_add_u32_e32 v5, 0x11a80, v42
	s_waitcnt lgkmcnt(12)
	v_mfma_f32_16x16x32_bf16 v[18:21], v[18:21], v[128:131], 0
	v_add_u32_e32 v10, 0x12480, v42
	ds_read_b64 v[76:77], v11
	ds_read_b64 v[120:121], v5
	ds_read_b64 v[122:123], v10
	v_add_u32_e32 v5, 0x11840, v43
	v_add_u32_e32 v40, 0x11d00, v42
	ds_read_b128 v[10:13], v5
	ds_read_b64 v[124:125], v40
	v_add_u32_e32 v5, 0x12700, v42
	ds_read_b64 v[126:127], v5
	s_waitcnt vmcnt(1)
	v_cvt_pk_bf16_f32 v132, v30, v31
	v_cvt_pk_bf16_f32 v133, v32, v33
	v_cvt_pk_bf16_f32 v134, v58, v59
	v_cvt_pk_bf16_f32 v135, v60, v61
	v_mov_b32_e32 v5, v4
	s_waitcnt lgkmcnt(11)
	v_mov_b32_e32 v40, v38
	v_mfma_f32_16x16x32_bf16 v[18:21], v[34:37], v[132:135], v[18:21]
	v_mov_b32_e32 v41, v39
	v_add_u32_e32 v34, 0x11f80, v42
	v_mov_b32_e32 v138, v38
	s_waitcnt lgkmcnt(10)
	v_mfma_f32_16x16x32_bf16 v[18:21], v[2:5], v[38:41], v[18:21]
	v_mov_b32_e32 v139, v39
	v_add_u32_e32 v2, 0x12980, v42
	s_add_i32 s75, s74, s75
	s_lshl_b32 s75, s75, 11
	s_add_i32 s49, s74, s49
	s_nop 2
	v_cvt_pk_bf16_f32 v136, v18, v19
	v_cvt_pk_bf16_f32 v137, v20, v21
	s_lshl_b32 s49, s49, 11
	s_andn2_b64 vcc, exec, s[16:17]
	s_waitcnt lgkmcnt(5)
	v_mfma_f32_16x16x32_bf16 v[38:41], v[74:77], v[136:139], v[26:29]
	s_nop 2
	ds_read_b64 v[26:27], v34
	ds_read_b64 v[28:29], v2
	v_add_u32_e32 v2, 0x11880, v43
	buffer_store_dword v6, v52, s[20:23], s75 offen sc1
	s_waitcnt lgkmcnt(5)
	v_mfma_f32_16x16x32_bf16 v[34:37], v[120:123], v[136:139], v[22:25]
	ds_read_b128 v[18:21], v2
	s_add_i32 s75, s39, s74
	v_add_u32_e32 v2, 0x118c0, v43
	v_mfma_f32_16x16x32_bf16 v[22:25], v[62:65], v[128:131], 0
	s_lshl_b32 s75, s75, 11
	ds_read_b128 v[42:45], v2
	buffer_store_dword v7, v52, s[20:23], s75 offen sc1
	v_mfma_f32_16x16x32_bf16 v[22:25], v[66:69], v[132:135], v[22:25]
	s_sub_i32 s75, s74, s88
	s_lshl_b32 s75, s75, 11
	s_addk_i32 s75, 0x1000
	s_waitcnt lgkmcnt(4)
	v_mfma_f32_16x16x32_bf16 v[30:33], v[124:127], v[136:139], v[30:33]
	buffer_store_dword v8, v52, s[20:23], s75 offen sc1
	buffer_store_dword v9, v52, s[20:23], s49 offen sc1
	s_mov_b32 s49, s45
	s_waitcnt lgkmcnt(2)
	v_mfma_f32_16x16x32_bf16 v[26:29], v[26:29], v[136:139], v[58:61]
	v_mfma_f32_16x16x32_bf16 v[22:25], v[70:73], v[136:139], v[22:25]
	s_cbranch_vccnz .LBB0_2947
	s_lshl_b32 s47, s46, 4
	s_add_i32 s47, s42, s47
	s_add_i32 s49, s47, 16
	s_mov_b32 s48, 0
	s_mov_b32 s47, 3
	s_branch .LBB0_2947
.LBB0_2952:
	ds_read_b64 v[2:3], v4 offset:408
	s_and_b32 s16, s72, 0x3fffff0
	s_lshl_b32 s17, s88, 3
	s_or_b32 s18, s17, s16
	s_or_b32 s18, s18, s26
	s_waitcnt lgkmcnt(0)
	v_readfirstlane_b32 s16, v2
	v_lshl_or_b32 v2, s18, 6, v49
	v_readfirstlane_b32 s17, v3
	v_ashrrev_i32_e32 v3, 31, v2
	v_lshlrev_b64 v[2:3], 8, v[2:3]
	v_lshl_add_u64 v[2:3], s[16:17], 0, v[2:3]
	v_lshlrev_b32_e32 v22, 2, v46
	v_mov_b32_e32 v23, v4
	v_lshl_add_u64 v[2:3], v[2:3], 0, v[22:23]
	v_lshl_add_u64 v[22:23], v[2:3], 0, s[34:35]
	v_add_co_u32_e32 v2, vcc, 0x2e80000, v2
	s_mov_b64 s[16:17], 0
	s_nop 0
	v_addc_co_u32_e32 v3, vcc, 0, v3, vcc
	global_store_dwordx4 v[2:3], v[6:9], off sc1
	global_store_dwordx4 v[22:23], v[10:13], off offset:64 sc1
	global_store_dwordx4 v[22:23], v[14:17], off offset:128 sc1
	global_store_dwordx4 v[22:23], v[18:21], off offset:192 sc1

.LBB0_2976:
	s_mul_hi_i32 s2, s57, 0x2aaaaaab
	s_lshr_b32 s3, s2, 31
	s_ashr_i32 s2, s2, 3
	s_add_i32 s8, s2, s3
	s_mul_i32 s2, s8, 0xffffe800
	s_add_i32 s2, s14, s2
	s_ashr_i32 s3, s2, 31
	s_lshl_b32 s8, s8, 7
	s_ashr_i32 s9, s8, 31
	s_lshl_b64 s[24:25], s[2:3], 8
	s_add_u32 s24, s10, s24
	s_addc_u32 s25, s11, s25
	s_lshl_b64 s[26:27], s[8:9], 8
	s_add_u32 s26, s12, s26
	v_lshl_add_u64 v[2:3], s[24:25], 0, v[34:35]
	s_mov_b32 m0, s15
	s_addc_u32 s27, s13, s27
	v_lshl_add_u64 v[2:3], v[2:3], 0, v[36:37]
	v_lshl_add_u64 v[4:5], s[24:25], 0, v[38:39]
	global_load_lds_dwordx4 v[2:3], off
	v_lshl_add_u64 v[4:5], v[4:5], 0, v[36:37]
	s_mov_b32 m0, s16
	v_lshl_add_u64 v[6:7], s[26:27], 0, v[34:35]
	global_load_lds_dwordx4 v[4:5], off
	v_lshl_add_u64 v[6:7], v[6:7], 0, v[36:37]
	s_mov_b32 m0, s17
	v_lshl_add_u64 v[8:9], s[26:27], 0, v[38:39]
	global_load_lds_dwordx4 v[6:7], off
	v_lshl_add_u64 v[8:9], v[8:9], 0, v[36:37]
	s_mov_b32 m0, s18
	v_lshl_add_u64 v[2:3], v[2:3], 0, s[6:7]
	global_load_lds_dwordx4 v[8:9], off
	s_mov_b32 m0, s19
	s_nop 0
	global_load_lds_dwordx4 v[2:3], off
	v_lshl_add_u64 v[2:3], v[4:5], 0, s[6:7]
	s_mov_b32 m0, s20
	s_nop 0
	global_load_lds_dwordx4 v[2:3], off
	v_lshl_add_u64 v[2:3], v[6:7], 0, s[6:7]
	s_mov_b32 m0, s21
	s_nop 0
	global_load_lds_dwordx4 v[2:3], off
	v_lshl_add_u64 v[2:3], v[8:9], 0, s[6:7]
	s_mov_b32 m0, s22
	s_nop 0
	global_load_lds_dwordx4 v[2:3], off
	s_waitcnt vmcnt(4)
	s_barrier
	ds_read_b128 v[2:5], v48 offset:17408
	ds_read_b128 v[6:9], v47 offset:1024
	ds_read_b128 v[10:13], v47 offset:2048
	ds_read_b128 v[14:17], v48 offset:18432
	ds_read_b128 v[22:25], v48 offset:19456
	ds_read_b128 v[26:29], v48 offset:20480
	ds_read_b128 v[30:33], v47 offset:3072
	ds_read_b128 v[40:43], v47 offset:4096
	ds_read_b128 v[54:57], v47 offset:5120
	ds_read_b128 v[58:61], v47 offset:6144
	ds_read_b128 v[66:69], v47 offset:7168
	ds_read_b128 v[70:73], v47 offset:8192
	s_waitcnt lgkmcnt(0)
	v_mfma_f32_16x16x32_bf16 v[18:21], v[2:5], v[6:9], 0
	s_waitcnt lgkmcnt(0)
	s_barrier
	v_mfma_f32_16x16x32_bf16 v[6:9], v[22:25], v[6:9], 0
	s_waitcnt vmcnt(0)
	s_barrier
	v_mfma_f32_16x16x32_bf16 v[50:53], v[2:5], v[30:33], 0
	v_mfma_f32_16x16x32_bf16 v[30:33], v[22:25], v[30:33], 0
	v_mfma_f32_16x16x32_bf16 v[62:65], v[2:5], v[54:57], 0
	v_mfma_f32_16x16x32_bf16 v[2:5], v[2:5], v[66:69], 0
	v_mfma_f32_16x16x32_bf16 v[18:21], v[14:17], v[10:13], v[18:21]
	v_mfma_f32_16x16x32_bf16 v[6:9], v[26:29], v[10:13], v[6:9]
	v_mfma_f32_16x16x32_bf16 v[10:13], v[14:17], v[40:43], v[50:53]
	v_mfma_f32_16x16x32_bf16 v[30:33], v[26:29], v[40:43], v[30:33]
	v_mfma_f32_16x16x32_bf16 v[40:43], v[14:17], v[58:61], v[62:65]
	v_mfma_f32_16x16x32_bf16 v[2:5], v[14:17], v[70:73], v[2:5]
	ds_read_b128 v[14:17], v48 offset:50176
	v_mfma_f32_16x16x32_bf16 v[54:57], v[22:25], v[54:57], 0
	v_mfma_f32_16x16x32_bf16 v[22:25], v[22:25], v[66:69], 0
	v_mfma_f32_16x16x32_bf16 v[50:53], v[26:29], v[58:61], v[54:57]
	v_mfma_f32_16x16x32_bf16 v[22:25], v[26:29], v[70:73], v[22:25]
	ds_read_b128 v[26:29], v47 offset:33792
	s_nop 3
	ds_read_b128 v[54:57], v47 offset:34816
	ds_read_b128 v[58:61], v48 offset:51200
	ds_read_b128 v[62:65], v48 offset:52224
	ds_read_b128 v[66:69], v48 offset:53248
	s_waitcnt lgkmcnt(0)
	v_mfma_f32_16x16x32_bf16 v[18:21], v[14:17], v[26:29], v[18:21]
	v_mfma_f32_16x16x32_bf16 v[6:9], v[62:65], v[26:29], v[6:9]
	ds_read_b128 v[26:29], v47 offset:35840
	ds_read_b128 v[70:73], v47 offset:36864
	s_waitcnt lgkmcnt(0)
	v_mfma_f32_16x16x32_bf16 v[10:13], v[14:17], v[26:29], v[10:13]
	v_mfma_f32_16x16x32_bf16 v[74:77], v[62:65], v[26:29], v[30:33]
	ds_read_b128 v[26:29], v47 offset:37888
	ds_read_b128 v[78:81], v47 offset:38912
	s_waitcnt lgkmcnt(0)
	v_mfma_f32_16x16x32_bf16 v[40:43], v[14:17], v[26:29], v[40:43]
	v_mfma_f32_16x16x32_bf16 v[50:53], v[62:65], v[26:29], v[50:53]
	ds_read_b128 v[26:29], v47 offset:39936
	ds_read_b128 v[82:85], v47 offset:40960
	s_waitcnt lgkmcnt(0)
	s_barrier
	s_waitcnt lgkmcnt(0)
	v_mfma_f32_16x16x32_bf16 v[2:5], v[14:17], v[26:29], v[2:5]
	v_mfma_f32_16x16x32_bf16 v[62:65], v[62:65], v[26:29], v[22:25]
	v_mfma_f32_16x16x32_bf16 v[14:17], v[58:61], v[78:81], v[40:43]
	s_nop 2
	v_add_u32_e32 v42, s2, v1
	v_ashrrev_i32_e32 v43, 31, v42
	v_mfma_f32_16x16x32_bf16 v[26:29], v[66:69], v[54:57], v[6:9]
	v_or_b32_e32 v40, s8, v46
	v_cmp_gt_i32_e32 vcc, s23, v40
	v_ashrrev_i32_e32 v41, 31, v40
	v_mfma_f32_16x16x32_bf16 v[6:9], v[58:61], v[82:85], v[2:5]
	s_nop 2
	v_lshlrev_b64 v[2:3], 11, v[42:43]
	v_mfma_f32_16x16x32_bf16 v[30:33], v[58:61], v[54:57], v[18:21]
	v_lshl_add_u64 v[44:45], s[4:5], 0, v[2:3]
	v_mfma_f32_16x16x32_bf16 v[22:25], v[58:61], v[70:73], v[10:13]
	v_mfma_f32_16x16x32_bf16 v[18:21], v[66:69], v[70:73], v[74:77]
	v_mfma_f32_16x16x32_bf16 v[10:13], v[66:69], v[78:81], v[50:53]
	v_mfma_f32_16x16x32_bf16 v[2:5], v[66:69], v[82:85], v[62:65]
	s_and_saveexec_b64 s[2:3], vcc
	s_cbranch_execz .LBB0_2978
	v_lshl_add_u64 v[50:51], v[40:41], 2, v[44:45]
	global_store_dwordx4 v[50:51], v[30:33], off sc1
.LBB0_2978:
	s_or_b64 exec, exec, s[2:3]
	s_nop 0
	v_or_b32_e32 v30, 16, v40
	v_cmp_gt_i32_e64 s[2:3], s23, v30
	s_and_saveexec_b64 s[8:9], s[2:3]
	s_cbranch_execz .LBB0_2980
	v_lshl_add_u64 v[30:31], v[40:41], 2, v[44:45]
	global_store_dwordx4 v[30:31], v[26:29], off offset:64 sc1
.LBB0_2980:
	s_or_b64 exec, exec, s[8:9]
	s_nop 0
	v_add_u32_e32 v26, 16, v42
	v_ashrrev_i32_e32 v27, 31, v26
	v_lshlrev_b64 v[26:27], 11, v[26:27]
	v_lshl_add_u64 v[26:27], s[4:5], 0, v[26:27]
	s_and_saveexec_b64 s[8:9], vcc
	s_cbranch_execz .LBB0_2982
	v_lshl_add_u64 v[28:29], v[40:41], 2, v[26:27]
	global_store_dwordx4 v[28:29], v[22:25], off sc1

.LBB0_2984:
	s_or_b64 exec, exec, s[8:9]
	s_nop 0
	v_add_u32_e32 v18, 32, v42
	v_ashrrev_i32_e32 v19, 31, v18
	v_lshlrev_b64 v[18:19], 11, v[18:19]
	v_lshl_add_u64 v[18:19], s[4:5], 0, v[18:19]
	s_and_saveexec_b64 s[8:9], vcc
	s_cbranch_execz .LBB0_2986
	v_lshl_add_u64 v[20:21], v[40:41], 2, v[18:19]
	global_store_dwordx4 v[20:21], v[14:17], off sc1

.LBB0_2988:
	s_or_b64 exec, exec, s[8:9]
	s_nop 0
	v_add_u32_e32 v10, 48, v42
	v_ashrrev_i32_e32 v11, 31, v10
	v_lshlrev_b64 v[10:11], 11, v[10:11]
	v_lshl_add_u64 v[10:11], s[4:5], 0, v[10:11]
	s_and_saveexec_b64 s[8:9], vcc
	s_cbranch_execz .LBB0_2990
	v_lshl_add_u64 v[12:13], v[40:41], 2, v[10:11]
	global_store_dwordx4 v[12:13], v[6:9], off sc1
.LBB0_2990:
	s_or_b64 exec, exec, s[8:9]
	s_and_saveexec_b64 s[8:9], s[2:3]
	s_cbranch_execz .LBB0_2975
	v_lshl_add_u64 v[6:7], v[40:41], 2, v[10:11]
	global_store_dwordx4 v[6:7], v[2:5], off offset:64 sc1
	s_branch .LBB0_2975
.LBB0_2992:
	s_mov_b64 s[2:3], 0

.LBB0_2998:
	s_add_i32 s25, s27, s25
	s_lshl_b32 s25, s25, 11
	s_nop 4
	buffer_store_dword v22, v1, s[4:7], s25 offen sc1
	s_add_i32 s25, s16, s27
	s_lshl_b32 s25, s25, 11
	buffer_store_dword v23, v1, s[4:7], s25 offen sc1
	s_sub_i32 s25, s27, s15
	s_lshl_b32 s25, s25, 11
	s_addk_i32 s25, 0x1000
	buffer_store_dword v24, v1, s[4:7], s25 offen sc1
	s_add_i32 s25, s27, s26
	s_lshl_b32 s25, s25, 11
	s_add_i32 s21, s21, 2
	s_addk_i32 s22, 0x7000
	s_sub_i32 s24, s24, 32
	s_add_i32 s23, s23, 32
	v_pk_mul_f32 v[20:21], v[12:13], v[20:21]
	v_pk_mul_f32 v[18:19], v[10:11], v[18:19]
	v_pk_mul_f32 v[16:17], v[16:17], v[32:33]
	v_pk_mul_f32 v[14:15], v[14:15], v[30:31]
	s_waitcnt lgkmcnt(1)
	v_pk_mul_f32 v[12:13], v[28:29], v[36:37]
	v_pk_mul_f32 v[10:11], v[26:27], v[34:35]
	s_waitcnt lgkmcnt(0)
	v_pk_mul_f32 v[8:9], v[8:9], v[40:41]
	v_pk_mul_f32 v[6:7], v[6:7], v[38:39]
	s_cmp_eq_u32 s22, 0
	buffer_store_dword v25, v1, s[4:7], s25 offen sc1
	s_cbranch_scc1 .LBB0_2996

.LBB0_3001:
	s_add_i32 s28, s27, s28
	s_lshl_b32 s28, s28, 11
	s_nop 4
	buffer_store_dword v6, v1, s[4:7], s28 offen sc1
	v_add_u32_e32 v3, 0x11800, v53
	v_add_u32_e32 v5, 0x11820, v53
	v_add_u32_e32 v6, 0x12100, v53
	s_waitcnt lgkmcnt(3)
	v_pk_mul_f32 v[22:23], v[38:39], v[22:23]
	s_waitcnt lgkmcnt(1)
	v_pk_mul_f32 v[38:39], v[30:31], v[10:11]
	s_waitcnt lgkmcnt(0)
	v_pk_mul_f32 v[58:59], v[28:29], v[20:21]
	v_pk_mul_f32 v[56:57], v[26:27], v[18:19]
	v_add_u32_e32 v10, 0x12120, v53
	ds_read_b64 v[18:19], v3
	ds_read_b64 v[20:21], v5
	ds_read_b64 v[60:61], v6
	ds_read_b64 v[62:63], v10
	v_add_u32_e32 v3, 0x11840, v53
	v_add_u32_e32 v5, 0x11860, v53
	v_add_u32_e32 v6, 0x12140, v53
	v_pk_mul_f32 v[24:25], v[40:41], v[24:25]
	v_pk_mul_f32 v[36:37], v[36:37], v[16:17]
	v_pk_mul_f32 v[34:35], v[34:35], v[14:15]
	v_add_u32_e32 v10, 0x12160, v53
	ds_read_b64 v[26:27], v3
	ds_read_b64 v[28:29], v5
	ds_read_b64 v[64:65], v6
	ds_read_b64 v[66:67], v10
	v_add_u32_e32 v3, 0x11800, v54
	v_add_u32_e32 v5, 0x12c00, v52
	v_add_u32_e32 v6, 0x11800, v2
	v_add_u32_e32 v10, 0x11820, v2
	ds_read_b64 v[30:31], v3
	ds_read_b64 v[2:3], v5
	ds_read_b64 v[68:69], v6
	ds_read_b64 v[70:71], v10
	v_add_u32_e32 v5, 0x11800, v55
	v_add_u32_e32 v6, 0x11800, v52
	v_cvt_pk_bf16_f32 v84, v22, v23
	v_cvt_pk_bf16_f32 v85, v24, v25
	v_cvt_pk_bf16_f32 v86, v34, v35
	v_cvt_pk_bf16_f32 v87, v36, v37
	v_pk_mul_f32 v[40:41], v[32:33], v[12:13]
	v_add_u32_e32 v14, 0x12200, v52
	ds_read_b64 v[72:73], v6
	ds_read_b128 v[10:13], v5
	v_add_u32_e32 v5, 0x11a80, v52
	s_waitcnt lgkmcnt(12)
	v_mfma_f32_16x16x32_bf16 v[18:21], v[18:21], v[84:87], 0
	v_add_u32_e32 v6, 0x12480, v52
	ds_read_b64 v[74:75], v14
	ds_read_b64 v[76:77], v5
	ds_read_b64 v[78:79], v6
	v_add_u32_e32 v5, 0x11840, v55
	v_add_u32_e32 v6, 0x11d00, v52
	ds_read_b128 v[14:17], v5
	ds_read_b64 v[80:81], v6
	v_add_u32_e32 v5, 0x12700, v52
	ds_read_b64 v[82:83], v5
	v_cvt_pk_bf16_f32 v88, v38, v39
	v_cvt_pk_bf16_f32 v89, v40, v41
	v_cvt_pk_bf16_f32 v90, v56, v57
	v_cvt_pk_bf16_f32 v91, v58, v59
	v_mov_b32_e32 v5, v4
	s_waitcnt lgkmcnt(11)
	v_mov_b32_e32 v32, v30
	v_mfma_f32_16x16x32_bf16 v[18:21], v[26:29], v[88:91], v[18:21]
	v_mov_b32_e32 v33, v31
	v_add_u32_e32 v6, 0x11f80, v52
	v_mov_b32_e32 v94, v30
	s_waitcnt lgkmcnt(10)
	v_mfma_f32_16x16x32_bf16 v[18:21], v[2:5], v[30:33], v[18:21]
	v_mov_b32_e32 v95, v31
	v_add_u32_e32 v2, 0x12980, v52
	s_add_i32 s28, s16, s27
	s_lshl_b32 s28, s28, 11
	s_add_i32 s26, s27, s26
	s_nop 2
	v_cvt_pk_bf16_f32 v92, v18, v19
	v_cvt_pk_bf16_f32 v93, v20, v21
	s_lshl_b32 s26, s26, 11
	s_andn2_b64 vcc, exec, s[2:3]
	s_waitcnt lgkmcnt(5)
	v_mfma_f32_16x16x32_bf16 v[18:21], v[72:75], v[92:95], v[22:25]
	s_nop 2
	ds_read_b64 v[22:23], v6
	ds_read_b64 v[24:25], v2
	buffer_store_dword v7, v1, s[4:7], s28 offen sc1
	s_sub_i32 s28, s27, s15
	s_waitcnt lgkmcnt(5)
	v_mfma_f32_16x16x32_bf16 v[30:33], v[76:79], v[92:95], v[34:37]
	v_add_u32_e32 v2, 0x11880, v55
	s_lshl_b32 s28, s28, 11
	ds_read_b128 v[26:29], v2
	s_waitcnt lgkmcnt(3)
	v_mfma_f32_16x16x32_bf16 v[34:37], v[80:83], v[92:95], v[38:41]
	s_addk_i32 s28, 0x1000
	v_add_u32_e32 v2, 0x118c0, v55
	buffer_store_dword v8, v1, s[4:7], s28 offen sc1
	s_waitcnt lgkmcnt(1)
	v_mfma_f32_16x16x32_bf16 v[38:41], v[22:25], v[92:95], v[56:59]
	buffer_store_dword v9, v1, s[4:7], s26 offen sc1
	ds_read_b128 v[6:9], v2
	s_mov_b32 s26, 0
	v_mfma_f32_16x16x32_bf16 v[22:25], v[60:63], v[84:87], 0
	s_mov_b32 s27, s24
	v_mfma_f32_16x16x32_bf16 v[22:25], v[64:67], v[88:91], v[22:25]
	v_mfma_f32_16x16x32_bf16 v[22:25], v[68:71], v[92:95], v[22:25]
	s_cbranch_vccnz .LBB0_2998
	s_lshl_b32 s25, s21, 4
	s_add_i32 s25, s20, s25
	s_add_i32 s27, s25, 16
	s_mov_b32 s25, 0
	s_mov_b32 s26, 3
	s_branch .LBB0_2998

.LBB0_3024:
	s_cmp_lt_i32 s59, 20
	s_waitcnt vmcnt(0)
	s_barrier
	s_cbranch_scc1 .LBB0_3078
	s_waitcnt vmcnt(0)
	s_barrier
	s_and_saveexec_b64 s[2:3], s[0:1]
	s_cbranch_execz .LBB0_3077
	s_waitcnt vmcnt(0) lgkmcnt(0)
	v_mov_b32_e32 v241, 0
	v_lshlrev_b32_e64 v254, 8, s31
	v_mov_b32_e32 v247, 1
	v_mov_b32_e32 v246, 0x3600
	global_atomic_add v248, v246, v247, s[60:61] sc0
